# substitution-chain instructions per V-half MFMA = 4
# baseline (speedup 1.0000x reference)
.Lmy_ck_nz:
	s_mov_b32 s100, 0xe000
	s_cmp_eq_u32 s23, 0
	s_cselect_b32 s100, 0x1c000, s100
	s_mov_b32 s101, 0x12e00
	s_cselect_b32 s101, 0x22100, s101
	s_lshl_b32 s96, s23, 13
	s_add_i32 s97, s96, 0x18000
	s_add_i32 s96, s96, 0xa000
	v_add_u32_e32 v225, s100, v1
	v_add_u32_e32 v236, s100, v0
	v_add_u32_e32 v34, s100, v10
	v_add_u32_e32 v226, s100, v2
	v_add_u32_e32 v227, s100, v3
	v_add_u32_e32 v228, s100, v4
	v_add_u32_e32 v229, s100, v5
	v_add_u32_e32 v237, s100, v6
	v_add_u32_e32 v238, s100, v7
	v_add_u32_e32 v230, s96, v8
	v_add_u32_e32 v239, s96, v9
	v_add_u32_e32 v231, s97, v8
	v_add_u32_e32 v26, s101, v1
	v_add_u32_e32 v27, s101, v0
	v_add_u32_e32 v35, s101, v10
	v_add_u32_e32 v28, s101, v2
	v_add_u32_e32 v29, s101, v3
	v_add_u32_e32 v30, s101, v4
	v_add_u32_e32 v31, s101, v5
	v_add_u32_e32 v32, s101, v6
	v_add_u32_e32 v33, s101, v7
	ds_read_b64 v[80:81], v237
	ds_read_b64 v[82:83], v238
	ds_read_b32 v36, v239
	ds_read_b32 v37, v239 offset:256
	ds_read_b128 v[88:91], v225
	ds_read_b128 v[92:95], v225 offset:1024
	ds_read_b128 v[96:99], v225 offset:2048
	ds_read_b128 v[100:103], v225 offset:3072
	ds_read_b32 v104, v227 offset:4
	ds_read_b32 v105, v227 offset:76
	ds_read_b64 v[106:107], v227 offset:8
	ds_read_b64 v[108:109], v227 offset:40
	ds_read_b32 v126, v229 offset:4
	ds_read_b32 v127, v229 offset:76
	ds_read_b64 v[128:129], v229 offset:8
	ds_read_b64 v[130:131], v229 offset:40
	ds_read_b64 v[110:111], v228
	ds_read_b64 v[112:113], v228 offset:32
	ds_read_b64 v[114:115], v228 offset:64
	ds_read_b64 v[116:117], v228 offset:96
	ds_read_b64 v[118:119], v228 offset:8
	ds_read_b64 v[120:121], v228 offset:40
	ds_read_b64 v[122:123], v228 offset:72
	ds_read_b64 v[124:125], v228 offset:104
	s_waitcnt lgkmcnt(15)
	v_mfma_f32_16x16x4_f32 v[240:243], v80, v36, 0
	v_mfma_f32_16x16x4_f32 v[240:243], v81, v37, v[240:243]
	v_mfma_f32_16x16x4_f32 v[240:243], v88, v208, v[240:243]
	ds_read_b64 v[186:187], v34
	ds_read_b64 v[190:191], v34 offset:1024
	v_mfma_f32_16x16x4_f32 v[244:247], v89, v209, 0
	ds_read_b64 v[194:195], v34 offset:2048
	ds_read_b64 v[198:199], v34 offset:3072
	v_mfma_f32_16x16x4_f32 v[240:243], v90, v210, v[240:243]
	ds_read_b64 v[184:185], v236
	ds_read_b64 v[188:189], v236 offset:1024
	ds_read_b64 v[132:133], v237 offset:9984
	v_mfma_f32_16x16x4_f32 v[244:247], v91, v211, v[244:247]
	ds_read_b64 v[134:135], v238 offset:9984
	ds_read_b64 v[192:193], v236 offset:2048
	ds_read_b64 v[196:197], v236 offset:3072
	v_mfma_f32_16x16x4_f32 v[240:243], v92, v212, v[240:243]
	ds_read_b32 v38, v239 offset:2048
	ds_read_b32 v39, v239 offset:2304
	ds_read_b128 v[140:143], v225 offset:9984
	v_mfma_f32_16x16x4_f32 v[244:247], v93, v213, v[244:247]
	ds_read_b128 v[144:147], v225 offset:11008
	ds_read_b128 v[148:151], v225 offset:12032
	ds_read_b128 v[152:155], v225 offset:13056
	v_mfma_f32_16x16x4_f32 v[240:243], v94, v214, v[240:243]
	ds_read_b32 v156, v227 offset:9988
	ds_read_b32 v157, v227 offset:10060
	v_mfma_f32_16x16x4_f32 v[244:247], v95, v215, v[244:247]
	ds_read_b64 v[158:159], v227 offset:9992
	ds_read_b64 v[160:161], v227 offset:10024
	v_mfma_f32_16x16x4_f32 v[240:243], v96, v216, v[240:243]
	ds_read_b32 v178, v229 offset:9988
	ds_read_b32 v179, v229 offset:10060
	v_mfma_f32_16x16x4_f32 v[244:247], v97, v217, v[244:247]
	ds_read_b64 v[180:181], v229 offset:9992
	ds_read_b64 v[182:183], v229 offset:10024
	v_mfma_f32_16x16x4_f32 v[240:243], v98, v218, v[240:243]
	ds_read_b64 v[162:163], v228 offset:9984
	ds_read_b64 v[164:165], v228 offset:10016
	v_mfma_f32_16x16x4_f32 v[244:247], v99, v219, v[244:247]
	ds_read_b64 v[166:167], v228 offset:10048
	ds_read_b64 v[168:169], v228 offset:10080
	v_mfma_f32_16x16x4_f32 v[240:243], v100, v220, v[240:243]
	ds_read_b64 v[170:171], v228 offset:9992
	ds_read_b64 v[172:173], v228 offset:10024
	v_mfma_f32_16x16x4_f32 v[244:247], v101, v221, v[244:247]
	ds_read_b64 v[174:175], v228 offset:10056
	ds_read_b64 v[176:177], v228 offset:10088
	v_mfma_f32_16x16x4_f32 v[240:243], v102, v222, v[240:243]
	v_mfma_f32_16x16x4_f32 v[244:247], v103, v223, v[244:247]
	s_waitcnt lgkmcnt(15)
	v_mfma_f32_16x16x4_f32 v[208:211], v186, v36, v[208:211]
	s_nop 2
	v_pk_add_f32 v[240:241], v[240:241], v[244:245]
	v_pk_add_f32 v[242:243], v[242:243], v[246:247]
	v_fmac_f32_e32 v241, v104, v240
	v_pk_fma_f32 v[242:243], v[106:107], v[240:241], v[242:243] op_sel:[0,0,0] op_sel_hi:[1,0,1]
	v_mfma_f32_16x16x4_f32 v[212:215], v190, v36, v[212:215]
	v_pk_fma_f32 v[242:243], v[108:109], v[240:241], v[242:243] op_sel:[0,1,0] op_sel_hi:[1,1,1]
	v_fmac_f32_e32 v243, v105, v242
	ds_bpermute_b32 v204, v232, v240
	ds_bpermute_b32 v205, v232, v241
	v_mfma_f32_16x16x4_f32 v[216:219], v194, v36, v[216:219]
	ds_bpermute_b32 v206, v232, v242
	ds_bpermute_b32 v207, v232, v243
	s_waitcnt lgkmcnt(2)
	v_pk_fma_f32 v[240:241], v[110:111], v[204:205], v[240:241] op_sel:[0,0,0] op_sel_hi:[1,0,1]
	v_pk_fma_f32 v[240:241], v[112:113], v[204:205], v[240:241] op_sel:[0,1,0] op_sel_hi:[1,1,1]
	v_mfma_f32_16x16x4_f32 v[72:75], v132, v38, 0
	s_waitcnt lgkmcnt(0)
	v_pk_fma_f32 v[240:241], v[114:115], v[206:207], v[240:241] op_sel:[0,0,0] op_sel_hi:[1,0,1]
	v_pk_fma_f32 v[240:241], v[116:117], v[206:207], v[240:241] op_sel:[0,1,0] op_sel_hi:[1,1,1]
	v_pk_fma_f32 v[242:243], v[118:119], v[204:205], v[242:243] op_sel:[0,0,0] op_sel_hi:[1,0,1]
	v_pk_fma_f32 v[242:243], v[120:121], v[204:205], v[242:243] op_sel:[0,1,0] op_sel_hi:[1,1,1]
	v_mfma_f32_16x16x4_f32 v[72:75], v133, v39, v[72:75]
	v_pk_fma_f32 v[242:243], v[122:123], v[206:207], v[242:243] op_sel:[0,0,0] op_sel_hi:[1,0,1]
	v_pk_fma_f32 v[242:243], v[124:125], v[206:207], v[242:243] op_sel:[0,1,0] op_sel_hi:[1,1,1]
	v_fmac_f32_e32 v241, v126, v240
	v_pk_fma_f32 v[242:243], v[128:129], v[240:241], v[242:243] op_sel:[0,0,0] op_sel_hi:[1,0,1]
	v_mfma_f32_16x16x4_f32 v[220:223], v198, v36, v[220:223]
	v_pk_fma_f32 v[242:243], v[130:131], v[240:241], v[242:243] op_sel:[0,1,0] op_sel_hi:[1,1,1]
	v_fmac_f32_e32 v243, v127, v242
	v_mov_b32_e32 v252, v240
	v_mov_b32_e32 v253, v241
	v_mfma_f32_16x16x4_f32 v[208:211], v187, v37, v[208:211]
	v_mov_b32_e32 v254, v242
	v_mov_b32_e32 v255, v243
	s_nop 0
	v_permlane32_swap_b32_e32 v252, v254
	v_permlane32_swap_b32_e32 v253, v255
	v_mfma_f32_16x16x4_f32 v[212:215], v191, v37, v[212:215]
	v_mfma_f32_16x16x4_f32 v[216:219], v195, v37, v[216:219]
	v_mfma_f32_16x16x4_f32 v[220:223], v199, v37, v[220:223]
	v_mfma_f32_16x16x4_f32 v[208:211], v184, v252, v[208:211]
	ds_read_b128 v[88:91], v226
	v_mfma_f32_16x16x4_f32 v[212:215], v188, v252, v[212:215]
	ds_read_b128 v[92:95], v226 offset:64
	v_mfma_f32_16x16x4_f32 v[216:219], v192, v252, v[216:219]
	ds_read_b128 v[96:99], v226 offset:128
	v_mfma_f32_16x16x4_f32 v[220:223], v196, v252, v[220:223]
	ds_read_b128 v[100:103], v226 offset:192
	v_mfma_f32_16x16x4_f32 v[208:211], v185, v253, v[208:211]
	v_mfma_f32_16x16x4_f32 v[212:215], v189, v253, v[212:215]
	v_mfma_f32_16x16x4_f32 v[216:219], v193, v253, v[216:219]
	v_mfma_f32_16x16x4_f32 v[220:223], v197, v253, v[220:223]
	v_mfma_f32_16x16x4_f32 v[248:251], v82, v252, v[240:243]
	v_mfma_f32_16x16x4_f32 v[248:251], v83, v253, v[248:251]
	s_waitcnt lgkmcnt(3)
	v_pk_mul_f32 v[208:209], v[208:209], v[88:89]
	v_pk_mul_f32 v[210:211], v[210:211], v[90:91]
	s_nop 0
	v_mfma_f32_16x16x4_f32 v[72:75], v140, v208, v[72:75]
	s_waitcnt lgkmcnt(2)
	v_pk_mul_f32 v[212:213], v[212:213], v[92:93]
	v_mfma_f32_16x16x4_f32 v[244:247], v141, v209, 0
	v_pk_mul_f32 v[214:215], v[214:215], v[94:95]
	v_mfma_f32_16x16x4_f32 v[72:75], v142, v210, v[72:75]
	s_waitcnt lgkmcnt(1)
	v_pk_mul_f32 v[216:217], v[216:217], v[96:97]
	v_mfma_f32_16x16x4_f32 v[244:247], v143, v211, v[244:247]
	v_pk_mul_f32 v[218:219], v[218:219], v[98:99]
	v_mfma_f32_16x16x4_f32 v[72:75], v144, v212, v[72:75]
	s_waitcnt lgkmcnt(0)
	v_pk_mul_f32 v[220:221], v[220:221], v[100:101]
	v_mfma_f32_16x16x4_f32 v[244:247], v145, v213, v[244:247]
	v_pk_mul_f32 v[222:223], v[222:223], v[102:103]
	v_mfma_f32_16x16x4_f32 v[72:75], v146, v214, v[72:75]
	s_mov_b64 exec, s[98:99]
	ds_write_b32 v231, v248
	ds_write_b32 v231, v249 offset:256
	ds_write_b32 v231, v250 offset:512
	ds_write_b32 v231, v251 offset:768
	s_mov_b64 exec, -1
	ds_read_b64 v[186:187], v34 offset:9984
	ds_read_b64 v[190:191], v34 offset:11008
	v_mfma_f32_16x16x4_f32 v[244:247], v147, v215, v[244:247]
	ds_read_b64 v[194:195], v34 offset:12032
	ds_read_b64 v[198:199], v34 offset:13056
	v_mfma_f32_16x16x4_f32 v[72:75], v148, v216, v[72:75]
	ds_read_b64 v[184:185], v236 offset:9984
	ds_read_b64 v[188:189], v236 offset:11008
	ds_read_b64 v[80:81], v32
	v_mfma_f32_16x16x4_f32 v[244:247], v149, v217, v[244:247]
	ds_read_b64 v[82:83], v33
	ds_read_b32 v36, v239 offset:4096
	ds_read_b64 v[192:193], v236 offset:12032
	v_mfma_f32_16x16x4_f32 v[72:75], v150, v218, v[72:75]
	ds_read_b64 v[196:197], v236 offset:13056
	ds_read_b32 v37, v239 offset:4352
	ds_read_b128 v[88:91], v26
	v_mfma_f32_16x16x4_f32 v[244:247], v151, v219, v[244:247]
	ds_read_b128 v[92:95], v26 offset:1024
	ds_read_b128 v[96:99], v26 offset:2048
	ds_read_b128 v[100:103], v26 offset:3072
	v_mfma_f32_16x16x4_f32 v[72:75], v152, v220, v[72:75]
	ds_read_b32 v104, v29 offset:4
	ds_read_b32 v105, v29 offset:76
	ds_read_b64 v[106:107], v29 offset:8
	v_mfma_f32_16x16x4_f32 v[244:247], v153, v221, v[244:247]
	ds_read_b64 v[108:109], v29 offset:40
	ds_read_b32 v126, v31 offset:4
	ds_read_b32 v127, v31 offset:76
	v_mfma_f32_16x16x4_f32 v[72:75], v154, v222, v[72:75]
	ds_read_b64 v[128:129], v31 offset:8
	ds_read_b64 v[130:131], v31 offset:40
	ds_read_b64 v[110:111], v30
	v_mfma_f32_16x16x4_f32 v[244:247], v155, v223, v[244:247]
	ds_read_b64 v[112:113], v30 offset:32
	ds_read_b64 v[114:115], v30 offset:64
	ds_read_b64 v[116:117], v30 offset:96
	ds_read_b64 v[118:119], v30 offset:8
	ds_read_b64 v[120:121], v30 offset:40
	ds_read_b64 v[122:123], v30 offset:72
	ds_read_b64 v[124:125], v30 offset:104
	s_waitcnt lgkmcnt(15)
	v_mfma_f32_16x16x4_f32 v[208:211], v186, v38, v[208:211]
	s_nop 1
	v_pk_add_f32 v[72:73], v[72:73], v[244:245]
	v_pk_add_f32 v[74:75], v[74:75], v[246:247]
	v_fmac_f32_e32 v73, v156, v72
	v_pk_fma_f32 v[74:75], v[158:159], v[72:73], v[74:75] op_sel:[0,0,0] op_sel_hi:[1,0,1]
	v_mfma_f32_16x16x4_f32 v[212:215], v190, v38, v[212:215]
	v_pk_fma_f32 v[74:75], v[160:161], v[72:73], v[74:75] op_sel:[0,1,0] op_sel_hi:[1,1,1]
	v_fmac_f32_e32 v75, v157, v74
	ds_bpermute_b32 v204, v232, v72
	ds_bpermute_b32 v205, v232, v73
	v_mfma_f32_16x16x4_f32 v[216:219], v194, v38, v[216:219]
	ds_bpermute_b32 v206, v232, v74
	ds_bpermute_b32 v207, v232, v75
	s_waitcnt lgkmcnt(2)
	v_pk_fma_f32 v[72:73], v[162:163], v[204:205], v[72:73] op_sel:[0,0,0] op_sel_hi:[1,0,1]
	v_pk_fma_f32 v[72:73], v[164:165], v[204:205], v[72:73] op_sel:[0,1,0] op_sel_hi:[1,1,1]
	v_mfma_f32_16x16x4_f32 v[240:243], v80, v36, 0
	s_waitcnt lgkmcnt(0)
	v_pk_fma_f32 v[72:73], v[166:167], v[206:207], v[72:73] op_sel:[0,0,0] op_sel_hi:[1,0,1]
	v_pk_fma_f32 v[72:73], v[168:169], v[206:207], v[72:73] op_sel:[0,1,0] op_sel_hi:[1,1,1]
	v_pk_fma_f32 v[74:75], v[170:171], v[204:205], v[74:75] op_sel:[0,0,0] op_sel_hi:[1,0,1]
	v_pk_fma_f32 v[74:75], v[172:173], v[204:205], v[74:75] op_sel:[0,1,0] op_sel_hi:[1,1,1]
	v_mfma_f32_16x16x4_f32 v[240:243], v81, v37, v[240:243]
	v_pk_fma_f32 v[74:75], v[174:175], v[206:207], v[74:75] op_sel:[0,0,0] op_sel_hi:[1,0,1]
	v_pk_fma_f32 v[74:75], v[176:177], v[206:207], v[74:75] op_sel:[0,1,0] op_sel_hi:[1,1,1]
	v_fmac_f32_e32 v73, v178, v72
	v_pk_fma_f32 v[74:75], v[180:181], v[72:73], v[74:75] op_sel:[0,0,0] op_sel_hi:[1,0,1]
	v_mfma_f32_16x16x4_f32 v[220:223], v198, v38, v[220:223]
	v_pk_fma_f32 v[74:75], v[182:183], v[72:73], v[74:75] op_sel:[0,1,0] op_sel_hi:[1,1,1]
	v_fmac_f32_e32 v75, v179, v74
	v_mov_b32_e32 v252, v72
	v_mov_b32_e32 v253, v73
	v_mfma_f32_16x16x4_f32 v[208:211], v187, v39, v[208:211]
	v_mov_b32_e32 v254, v74
	v_mov_b32_e32 v255, v75
	s_nop 0
	v_permlane32_swap_b32_e32 v252, v254
	v_permlane32_swap_b32_e32 v253, v255
	v_mfma_f32_16x16x4_f32 v[212:215], v191, v39, v[212:215]
	v_mfma_f32_16x16x4_f32 v[216:219], v195, v39, v[216:219]
	v_mfma_f32_16x16x4_f32 v[220:223], v199, v39, v[220:223]
	v_mfma_f32_16x16x4_f32 v[208:211], v184, v252, v[208:211]
	ds_read_b128 v[140:143], v226 offset:9984
	v_mfma_f32_16x16x4_f32 v[212:215], v188, v252, v[212:215]
	ds_read_b128 v[144:147], v226 offset:10048
	v_mfma_f32_16x16x4_f32 v[216:219], v192, v252, v[216:219]
	ds_read_b128 v[148:151], v226 offset:10112
	v_mfma_f32_16x16x4_f32 v[220:223], v196, v252, v[220:223]
	ds_read_b128 v[152:155], v226 offset:10176
	v_mfma_f32_16x16x4_f32 v[208:211], v185, v253, v[208:211]
	v_mfma_f32_16x16x4_f32 v[212:215], v189, v253, v[212:215]
	v_mfma_f32_16x16x4_f32 v[216:219], v193, v253, v[216:219]
	v_mfma_f32_16x16x4_f32 v[220:223], v197, v253, v[220:223]
	v_mfma_f32_16x16x4_f32 v[248:251], v134, v252, v[72:75]
	v_mfma_f32_16x16x4_f32 v[248:251], v135, v253, v[248:251]
	s_waitcnt lgkmcnt(3)
	v_pk_mul_f32 v[208:209], v[208:209], v[140:141]
	v_pk_mul_f32 v[210:211], v[210:211], v[142:143]
	s_nop 0
	v_mfma_f32_16x16x4_f32 v[240:243], v88, v208, v[240:243]
	s_waitcnt lgkmcnt(2)
	v_pk_mul_f32 v[212:213], v[212:213], v[144:145]
	v_mfma_f32_16x16x4_f32 v[244:247], v89, v209, 0
	v_pk_mul_f32 v[214:215], v[214:215], v[146:147]
	v_mfma_f32_16x16x4_f32 v[240:243], v90, v210, v[240:243]
	s_waitcnt lgkmcnt(1)
	v_pk_mul_f32 v[216:217], v[216:217], v[148:149]
	v_mfma_f32_16x16x4_f32 v[244:247], v91, v211, v[244:247]
	v_pk_mul_f32 v[218:219], v[218:219], v[150:151]
	v_mfma_f32_16x16x4_f32 v[240:243], v92, v212, v[240:243]
	s_waitcnt lgkmcnt(0)
	v_pk_mul_f32 v[220:221], v[220:221], v[152:153]
	v_mfma_f32_16x16x4_f32 v[244:247], v93, v213, v[244:247]
	v_pk_mul_f32 v[222:223], v[222:223], v[154:155]
	v_mfma_f32_16x16x4_f32 v[240:243], v94, v214, v[240:243]
	s_mov_b64 exec, s[98:99]
	ds_write_b32 v231, v248 offset:2048
	ds_write_b32 v231, v249 offset:2304
	ds_write_b32 v231, v250 offset:2560
	ds_write_b32 v231, v251 offset:2816
	s_mov_b64 exec, -1
	ds_read_b64 v[186:187], v35
	ds_read_b64 v[190:191], v35 offset:1024
	v_mfma_f32_16x16x4_f32 v[244:247], v95, v215, v[244:247]
	ds_read_b64 v[194:195], v35 offset:2048
	ds_read_b64 v[198:199], v35 offset:3072
	v_mfma_f32_16x16x4_f32 v[240:243], v96, v216, v[240:243]
	ds_read_b64 v[184:185], v27
	ds_read_b64 v[188:189], v27 offset:1024
	ds_read_b64 v[132:133], v32 offset:9984
	v_mfma_f32_16x16x4_f32 v[244:247], v97, v217, v[244:247]
	ds_read_b64 v[134:135], v33 offset:9984
	ds_read_b32 v38, v239 offset:6144
	ds_read_b64 v[192:193], v27 offset:2048
	v_mfma_f32_16x16x4_f32 v[240:243], v98, v218, v[240:243]
	ds_read_b64 v[196:197], v27 offset:3072
	ds_read_b32 v39, v239 offset:6400
	ds_read_b128 v[140:143], v26 offset:9984
	v_mfma_f32_16x16x4_f32 v[244:247], v99, v219, v[244:247]
	ds_read_b128 v[144:147], v26 offset:11008
	ds_read_b128 v[148:151], v26 offset:12032
	ds_read_b128 v[152:155], v26 offset:13056
	v_mfma_f32_16x16x4_f32 v[240:243], v100, v220, v[240:243]
	ds_read_b32 v156, v29 offset:9988
	ds_read_b32 v157, v29 offset:10060
	ds_read_b64 v[158:159], v29 offset:9992
	v_mfma_f32_16x16x4_f32 v[244:247], v101, v221, v[244:247]
	ds_read_b64 v[160:161], v29 offset:10024
	ds_read_b32 v178, v31 offset:9988
	ds_read_b32 v179, v31 offset:10060
	v_mfma_f32_16x16x4_f32 v[240:243], v102, v222, v[240:243]
	ds_read_b64 v[180:181], v31 offset:9992
	ds_read_b64 v[182:183], v31 offset:10024
	ds_read_b64 v[162:163], v30 offset:9984
	v_mfma_f32_16x16x4_f32 v[244:247], v103, v223, v[244:247]
	ds_read_b64 v[164:165], v30 offset:10016
	ds_read_b64 v[166:167], v30 offset:10048
	ds_read_b64 v[168:169], v30 offset:10080
	ds_read_b64 v[170:171], v30 offset:9992
	ds_read_b64 v[172:173], v30 offset:10024
	ds_read_b64 v[174:175], v30 offset:10056
	ds_read_b64 v[176:177], v30 offset:10088
	s_waitcnt lgkmcnt(15)
	v_mfma_f32_16x16x4_f32 v[208:211], v186, v36, v[208:211]
	s_nop 1
	v_pk_add_f32 v[240:241], v[240:241], v[244:245]
	v_pk_add_f32 v[242:243], v[242:243], v[246:247]
	v_fmac_f32_e32 v241, v104, v240
	v_pk_fma_f32 v[242:243], v[106:107], v[240:241], v[242:243] op_sel:[0,0,0] op_sel_hi:[1,0,1]
	v_mfma_f32_16x16x4_f32 v[212:215], v190, v36, v[212:215]
	v_pk_fma_f32 v[242:243], v[108:109], v[240:241], v[242:243] op_sel:[0,1,0] op_sel_hi:[1,1,1]
	v_fmac_f32_e32 v243, v105, v242
	ds_bpermute_b32 v204, v232, v240
	ds_bpermute_b32 v205, v232, v241
	v_mfma_f32_16x16x4_f32 v[216:219], v194, v36, v[216:219]
	ds_bpermute_b32 v206, v232, v242
	ds_bpermute_b32 v207, v232, v243
	s_waitcnt lgkmcnt(2)
	v_pk_fma_f32 v[240:241], v[110:111], v[204:205], v[240:241] op_sel:[0,0,0] op_sel_hi:[1,0,1]
	v_pk_fma_f32 v[240:241], v[112:113], v[204:205], v[240:241] op_sel:[0,1,0] op_sel_hi:[1,1,1]
	v_mfma_f32_16x16x4_f32 v[72:75], v132, v38, 0
	s_waitcnt lgkmcnt(0)
	v_pk_fma_f32 v[240:241], v[114:115], v[206:207], v[240:241] op_sel:[0,0,0] op_sel_hi:[1,0,1]
	v_pk_fma_f32 v[240:241], v[116:117], v[206:207], v[240:241] op_sel:[0,1,0] op_sel_hi:[1,1,1]
	v_pk_fma_f32 v[242:243], v[118:119], v[204:205], v[242:243] op_sel:[0,0,0] op_sel_hi:[1,0,1]
	v_pk_fma_f32 v[242:243], v[120:121], v[204:205], v[242:243] op_sel:[0,1,0] op_sel_hi:[1,1,1]
	v_mfma_f32_16x16x4_f32 v[72:75], v133, v39, v[72:75]
	v_pk_fma_f32 v[242:243], v[122:123], v[206:207], v[242:243] op_sel:[0,0,0] op_sel_hi:[1,0,1]
	v_pk_fma_f32 v[242:243], v[124:125], v[206:207], v[242:243] op_sel:[0,1,0] op_sel_hi:[1,1,1]
	v_fmac_f32_e32 v241, v126, v240
	v_pk_fma_f32 v[242:243], v[128:129], v[240:241], v[242:243] op_sel:[0,0,0] op_sel_hi:[1,0,1]
	v_mfma_f32_16x16x4_f32 v[220:223], v198, v36, v[220:223]
	v_pk_fma_f32 v[242:243], v[130:131], v[240:241], v[242:243] op_sel:[0,1,0] op_sel_hi:[1,1,1]
	v_fmac_f32_e32 v243, v127, v242
	v_mov_b32_e32 v252, v240
	v_mov_b32_e32 v253, v241
	v_mfma_f32_16x16x4_f32 v[208:211], v187, v37, v[208:211]
	v_mov_b32_e32 v254, v242
	v_mov_b32_e32 v255, v243
	s_nop 0
	v_permlane32_swap_b32_e32 v252, v254
	v_permlane32_swap_b32_e32 v253, v255
	v_mfma_f32_16x16x4_f32 v[212:215], v191, v37, v[212:215]
	v_mfma_f32_16x16x4_f32 v[216:219], v195, v37, v[216:219]
	v_mfma_f32_16x16x4_f32 v[220:223], v199, v37, v[220:223]
	v_mfma_f32_16x16x4_f32 v[208:211], v184, v252, v[208:211]
	ds_read_b128 v[88:91], v28
	v_mfma_f32_16x16x4_f32 v[212:215], v188, v252, v[212:215]
	ds_read_b128 v[92:95], v28 offset:64
	v_mfma_f32_16x16x4_f32 v[216:219], v192, v252, v[216:219]
	ds_read_b128 v[96:99], v28 offset:128
	v_mfma_f32_16x16x4_f32 v[220:223], v196, v252, v[220:223]
	ds_read_b128 v[100:103], v28 offset:192
	v_mfma_f32_16x16x4_f32 v[208:211], v185, v253, v[208:211]
	v_mfma_f32_16x16x4_f32 v[212:215], v189, v253, v[212:215]
	v_mfma_f32_16x16x4_f32 v[216:219], v193, v253, v[216:219]
	v_mfma_f32_16x16x4_f32 v[220:223], v197, v253, v[220:223]
	v_mfma_f32_16x16x4_f32 v[248:251], v82, v252, v[240:243]
	v_mfma_f32_16x16x4_f32 v[248:251], v83, v253, v[248:251]
	s_waitcnt lgkmcnt(3)
	v_pk_mul_f32 v[208:209], v[208:209], v[88:89]
	v_pk_mul_f32 v[210:211], v[210:211], v[90:91]
	s_nop 0
	v_mfma_f32_16x16x4_f32 v[72:75], v140, v208, v[72:75]
	s_waitcnt lgkmcnt(2)
	v_pk_mul_f32 v[212:213], v[212:213], v[92:93]
	v_mfma_f32_16x16x4_f32 v[244:247], v141, v209, 0
	v_pk_mul_f32 v[214:215], v[214:215], v[94:95]
	v_mfma_f32_16x16x4_f32 v[72:75], v142, v210, v[72:75]
	s_waitcnt lgkmcnt(1)
	v_pk_mul_f32 v[216:217], v[216:217], v[96:97]
	v_mfma_f32_16x16x4_f32 v[244:247], v143, v211, v[244:247]
	v_pk_mul_f32 v[218:219], v[218:219], v[98:99]
	v_mfma_f32_16x16x4_f32 v[72:75], v144, v212, v[72:75]
	s_waitcnt lgkmcnt(0)
	v_pk_mul_f32 v[220:221], v[220:221], v[100:101]
	v_mfma_f32_16x16x4_f32 v[244:247], v145, v213, v[244:247]
	v_pk_mul_f32 v[222:223], v[222:223], v[102:103]
	v_mfma_f32_16x16x4_f32 v[72:75], v146, v214, v[72:75]
	s_mov_b64 exec, s[98:99]
	ds_write_b32 v231, v248 offset:4096
	ds_write_b32 v231, v249 offset:4352
	ds_write_b32 v231, v250 offset:4608
	ds_write_b32 v231, v251 offset:4864
	s_mov_b64 exec, -1
	ds_read_b64 v[186:187], v35 offset:9984
	ds_read_b64 v[190:191], v35 offset:11008
	v_mfma_f32_16x16x4_f32 v[244:247], v147, v215, v[244:247]
	ds_read_b64 v[194:195], v35 offset:12032
	ds_read_b64 v[198:199], v35 offset:13056
	v_mfma_f32_16x16x4_f32 v[72:75], v148, v216, v[72:75]
	ds_read_b64 v[184:185], v27 offset:9984
	ds_read_b64 v[188:189], v27 offset:11008
	v_mfma_f32_16x16x4_f32 v[244:247], v149, v217, v[244:247]
	ds_read_b64 v[192:193], v27 offset:12032
	ds_read_b64 v[196:197], v27 offset:13056
	v_mfma_f32_16x16x4_f32 v[72:75], v150, v218, v[72:75]
	v_mfma_f32_16x16x4_f32 v[244:247], v151, v219, v[244:247]
	v_mfma_f32_16x16x4_f32 v[72:75], v152, v220, v[72:75]
	v_mfma_f32_16x16x4_f32 v[244:247], v153, v221, v[244:247]
	v_mfma_f32_16x16x4_f32 v[72:75], v154, v222, v[72:75]
	v_mfma_f32_16x16x4_f32 v[244:247], v155, v223, v[244:247]
	s_waitcnt lgkmcnt(7)
	v_mfma_f32_16x16x4_f32 v[208:211], v186, v38, v[208:211]
	s_nop 2
	v_pk_add_f32 v[72:73], v[72:73], v[244:245]
	v_pk_add_f32 v[74:75], v[74:75], v[246:247]
	v_fmac_f32_e32 v73, v156, v72
	v_pk_fma_f32 v[74:75], v[158:159], v[72:73], v[74:75] op_sel:[0,0,0] op_sel_hi:[1,0,1]
	s_waitcnt lgkmcnt(6)
	v_mfma_f32_16x16x4_f32 v[212:215], v190, v38, v[212:215]
	v_pk_fma_f32 v[74:75], v[160:161], v[72:73], v[74:75] op_sel:[0,1,0] op_sel_hi:[1,1,1]
	v_fmac_f32_e32 v75, v157, v74
	ds_bpermute_b32 v204, v232, v72
	ds_bpermute_b32 v205, v232, v73
	s_waitcnt lgkmcnt(7)
	v_mfma_f32_16x16x4_f32 v[216:219], v194, v38, v[216:219]
	ds_bpermute_b32 v206, v232, v74
	ds_bpermute_b32 v207, v232, v75
	s_waitcnt lgkmcnt(2)
	v_pk_fma_f32 v[72:73], v[162:163], v[204:205], v[72:73] op_sel:[0,0,0] op_sel_hi:[1,0,1]
	v_pk_fma_f32 v[72:73], v[164:165], v[204:205], v[72:73] op_sel:[0,1,0] op_sel_hi:[1,1,1]
	v_mfma_f32_16x16x4_f32 v[220:223], v198, v38, v[220:223]
	s_waitcnt lgkmcnt(0)
	v_pk_fma_f32 v[72:73], v[166:167], v[206:207], v[72:73] op_sel:[0,0,0] op_sel_hi:[1,0,1]
	v_pk_fma_f32 v[72:73], v[168:169], v[206:207], v[72:73] op_sel:[0,1,0] op_sel_hi:[1,1,1]
	v_pk_fma_f32 v[74:75], v[170:171], v[204:205], v[74:75] op_sel:[0,0,0] op_sel_hi:[1,0,1]
	v_pk_fma_f32 v[74:75], v[172:173], v[204:205], v[74:75] op_sel:[0,1,0] op_sel_hi:[1,1,1]
	v_mfma_f32_16x16x4_f32 v[208:211], v187, v39, v[208:211]
	v_pk_fma_f32 v[74:75], v[174:175], v[206:207], v[74:75] op_sel:[0,0,0] op_sel_hi:[1,0,1]
	v_pk_fma_f32 v[74:75], v[176:177], v[206:207], v[74:75] op_sel:[0,1,0] op_sel_hi:[1,1,1]
	v_fmac_f32_e32 v73, v178, v72
	v_pk_fma_f32 v[74:75], v[180:181], v[72:73], v[74:75] op_sel:[0,0,0] op_sel_hi:[1,0,1]
	v_mfma_f32_16x16x4_f32 v[212:215], v191, v39, v[212:215]
	v_pk_fma_f32 v[74:75], v[182:183], v[72:73], v[74:75] op_sel:[0,1,0] op_sel_hi:[1,1,1]
	v_fmac_f32_e32 v75, v179, v74
	v_mov_b32_e32 v252, v72
	v_mov_b32_e32 v253, v73
	v_mfma_f32_16x16x4_f32 v[216:219], v195, v39, v[216:219]
	v_mov_b32_e32 v254, v74
	v_mov_b32_e32 v255, v75
	s_nop 0
	v_permlane32_swap_b32_e32 v252, v254
	v_permlane32_swap_b32_e32 v253, v255
	v_mfma_f32_16x16x4_f32 v[220:223], v199, v39, v[220:223]
	v_mfma_f32_16x16x4_f32 v[208:211], v184, v252, v[208:211]
	ds_read_b128 v[140:143], v28 offset:9984
	v_mfma_f32_16x16x4_f32 v[212:215], v188, v252, v[212:215]
	ds_read_b128 v[144:147], v28 offset:10048
	v_mfma_f32_16x16x4_f32 v[216:219], v192, v252, v[216:219]
	ds_read_b128 v[148:151], v28 offset:10112
	v_mfma_f32_16x16x4_f32 v[220:223], v196, v252, v[220:223]
	ds_read_b128 v[152:155], v28 offset:10176
	v_mfma_f32_16x16x4_f32 v[208:211], v185, v253, v[208:211]
	v_mfma_f32_16x16x4_f32 v[212:215], v189, v253, v[212:215]
	v_mfma_f32_16x16x4_f32 v[216:219], v193, v253, v[216:219]
	v_mfma_f32_16x16x4_f32 v[220:223], v197, v253, v[220:223]
	v_mfma_f32_16x16x4_f32 v[248:251], v134, v252, v[72:75]
	v_mfma_f32_16x16x4_f32 v[248:251], v135, v253, v[248:251]
	s_waitcnt lgkmcnt(3)
	v_pk_mul_f32 v[208:209], v[208:209], v[140:141]
	v_pk_mul_f32 v[210:211], v[210:211], v[142:143]
	s_waitcnt lgkmcnt(2)
	v_pk_mul_f32 v[212:213], v[212:213], v[144:145]
	v_pk_mul_f32 v[214:215], v[214:215], v[146:147]
	s_waitcnt lgkmcnt(1)
	v_pk_mul_f32 v[216:217], v[216:217], v[148:149]
	v_pk_mul_f32 v[218:219], v[218:219], v[150:151]
	s_waitcnt lgkmcnt(0)
	v_pk_mul_f32 v[220:221], v[220:221], v[152:153]
	v_pk_mul_f32 v[222:223], v[222:223], v[154:155]
	s_mov_b64 exec, s[98:99]
	s_nop 0
	ds_write_b32 v231, v248 offset:6144
	ds_write_b32 v231, v249 offset:6400
	ds_write_b32 v231, v250 offset:6656
	ds_write_b32 v231, v251 offset:6912
	s_mov_b64 exec, -1
	s_branch .LBB0_655

.Lmy_ck_drE_h:
	s_waitcnt lgkmcnt(0)
	s_bfe_u32 s96, s62, 0x20006
	s_and_b32 s97, s96, 1
	s_mul_i32 s97, s97, 0x2700
	s_mov_b32 s101, 0x1c000
	s_mov_b32 s100, 0x6100
	s_bitcmp0_b32 s65, 0
	s_cselect_b32 s101, 0xe000, s101
	s_cselect_b32 s100, 0x4e00, s100
	s_cmp_gt_u32 s96, 1
	s_cselect_b32 s100, s100, 0
	s_add_i32 s97, s97, s101
	s_add_i32 s97, s97, s100
	s_mov_b32 s96, s97
	v_and_b32_e32 v72, 3, v233
	v_lshrrev_b32_e32 v73, 2, v233
	v_lshlrev_b32_e32 v72, 2, v72
	v_lshl_add_u32 v72, v73, 8, v72
	v_lshl_add_u32 v72, v234, 6, v72
	s_add_i32 s97, s96, 0x1000
	v_add_u32_e32 v78, s97, v72
	v_xor_b32_e32 v79, v224, v234
	v_lshl_add_u32 v79, v79, 4, s96
	ds_read_b128 v[96:99], v79
	ds_read_b128 v[100:103], v79 offset:1024
	ds_read_b128 v[104:107], v79 offset:2048
	ds_read_b128 v[108:111], v79 offset:3072
	ds_read_b32 v80, v78
	ds_read_b32 v81, v78 offset:16
	ds_read_b32 v82, v78 offset:32
	ds_read_b32 v83, v78 offset:48
	ds_read_b32 v84, v78 offset:1024
	ds_read_b32 v85, v78 offset:1040
	ds_read_b32 v86, v78 offset:1056
	ds_read_b32 v87, v78 offset:1072
	ds_read_b32 v88, v78 offset:2048
	ds_read_b32 v89, v78 offset:2064
	ds_read_b32 v90, v78 offset:2080
	ds_read_b32 v91, v78 offset:2096
	ds_read_b32 v92, v78 offset:3072
	ds_read_b32 v93, v78 offset:3088
	ds_read_b32 v94, v78 offset:3104
	ds_read_b32 v95, v78 offset:3120
	v_lshl_add_u32 v74, v224, 2, s96
	ds_write_b32 v74, v235 offset:9728
	v_add_u32_e32 v75, -1, v233
	v_mov_b32_e32 v76, -1
	v_cndmask_b32_e64 v75, v76, v75, s[98:99]
	v_cmp_lt_u32_e64 s[100:101], 7, v233
	v_add_u32_e32 v76, -8, v233
	v_and_b32_e32 v77, 1, v234
	v_cndmask_b32_e64 v75, v75, v76, s[100:101]
	v_lshlrev_b32_e32 v77, 2, v77
	v_sub_u32_e32 v76, v75, v77
	v_lshlrev_b32_e32 v77, 2, v234
	v_sub_u32_e32 v77, v233, v77
	v_add_u32_e32 v77, -1, v77
	s_waitcnt lgkmcnt(15)
	v_mfma_f32_16x16x4_f32 v[244:247], v80, v96, 0
	v_mfma_f32_16x16x4_f32 v[240:243], v81, v97, 0
	s_waitcnt lgkmcnt(14)
	v_mfma_f32_16x16x4_f32 v[244:247], v82, v98, v[244:247]
	s_waitcnt lgkmcnt(13)
	v_mfma_f32_16x16x4_f32 v[240:243], v83, v99, v[240:243]
	s_waitcnt lgkmcnt(12)
	v_mfma_f32_16x16x4_f32 v[244:247], v84, v100, v[244:247]
	s_waitcnt lgkmcnt(11)
	v_mfma_f32_16x16x4_f32 v[240:243], v85, v101, v[240:243]
	s_waitcnt lgkmcnt(10)
	v_mfma_f32_16x16x4_f32 v[244:247], v86, v102, v[244:247]
	s_waitcnt lgkmcnt(9)
	v_mfma_f32_16x16x4_f32 v[240:243], v87, v103, v[240:243]
	s_waitcnt lgkmcnt(8)
	v_mfma_f32_16x16x4_f32 v[244:247], v88, v104, v[244:247]
	s_waitcnt lgkmcnt(7)
	v_mfma_f32_16x16x4_f32 v[240:243], v89, v105, v[240:243]
	s_waitcnt lgkmcnt(6)
	v_mfma_f32_16x16x4_f32 v[244:247], v90, v106, v[244:247]
	s_waitcnt lgkmcnt(5)
	v_mfma_f32_16x16x4_f32 v[240:243], v91, v107, v[240:243]
	s_waitcnt lgkmcnt(4)
	v_mfma_f32_16x16x4_f32 v[244:247], v92, v108, v[244:247]
	s_waitcnt lgkmcnt(3)
	v_mfma_f32_16x16x4_f32 v[240:243], v93, v109, v[240:243]
	s_waitcnt lgkmcnt(2)
	v_mfma_f32_16x16x4_f32 v[244:247], v94, v110, v[244:247]
	s_waitcnt lgkmcnt(1)
	v_mfma_f32_16x16x4_f32 v[240:243], v95, v111, v[240:243]
	s_nop 9
	v_add_f32_e32 v244, v244, v240
	v_add_f32_e32 v245, v245, v241
	v_add_f32_e32 v246, v246, v242
	v_add_f32_e32 v247, v247, v243
	v_cmp_le_i32_e64 s[96:97], 0, v76
	v_cmp_le_i32_e64 s[100:101], 1, v76
	s_nop 0
	v_cndmask_b32_e64 v128, 0, v244, s[96:97]
	v_cndmask_b32_e64 v129, 0, v245, s[100:101]
	v_cmp_le_i32_e64 s[96:97], 2, v76
	v_cmp_le_i32_e64 s[100:101], 3, v76
	s_nop 0
	v_cndmask_b32_e64 v130, 0, v246, s[96:97]
	v_cndmask_b32_e64 v131, 0, v247, s[100:101]
	s_bfe_u32 s96, s62, 0x20006
	s_and_b32 s97, s96, 1
	s_mul_i32 s97, s97, 0x2700
	s_mov_b32 s101, 0x1c000
	s_mov_b32 s100, 0x6100
	s_bitcmp0_b32 s65, 0
	s_cselect_b32 s101, 0xe000, s101
	s_cselect_b32 s100, 0x4e00, s100
	s_cmp_gt_u32 s96, 1
	s_cselect_b32 s100, s100, 0
	s_add_i32 s97, s97, s101
	s_add_i32 s97, s97, s100
	v_xor_b32_e32 v74, v224, v234
	v_lshl_add_u32 v74, v74, 4, s97
	ds_write_b128 v74, v[128:131] offset:8448
	v_lshlrev_b32_e32 v75, 7, v234
	v_lshl_add_u32 v75, v233, 2, v75
	v_add_u32_e32 v75, s97, v75
	v_cmp_le_i32_e64 s[96:97], 0, v77
	v_cmp_le_i32_e64 s[100:101], 1, v77
	s_nop 0
	v_cndmask_b32_e64 v132, 0, v244, s[96:97]
	v_cndmask_b32_e64 v133, 0, v245, s[100:101]
	v_cmp_le_i32_e64 s[96:97], 2, v77
	v_cmp_le_i32_e64 s[100:101], 3, v77
	s_nop 0
	v_cndmask_b32_e64 v134, 0, v246, s[96:97]
	v_cndmask_b32_e64 v135, 0, v247, s[100:101]
	s_mov_b64 exec, 0x00ff00ff
	ds_write_b32 v75, v132 offset:9472
	ds_write_b32 v75, v133 offset:9504
	ds_write_b32 v75, v134 offset:9536
	ds_write_b32 v75, v135 offset:9568
	s_mov_b64 exec, -1
	s_setprio 0
	s_branch .LBB0_655
	s_nop 0
	s_nop 0
	s_nop 0
	s_nop 0
	s_nop 0
	s_nop 0
	s_nop 0
	s_nop 0
	s_nop 0
	s_nop 0
	s_nop 0
	s_nop 0
	s_nop 0
	s_nop 0
	s_nop 0
	s_nop 0
	s_nop 0
	s_nop 0
	s_nop 0
	s_nop 0
	s_nop 0
	s_nop 0
	s_nop 0
	s_nop 0
	s_nop 0
	s_nop 0
	s_nop 0
	s_nop 0
	s_nop 0
	s_nop 0
	s_nop 0
	s_nop 0
	s_nop 0
	s_nop 0
	s_nop 0
	s_nop 0
	s_nop 0
	s_nop 0
	s_nop 0
	s_nop 0
	s_nop 0
	s_nop 0
	s_nop 0
	s_nop 0
	s_nop 0
	s_nop 0
	s_nop 0
